# row passes: sample-row path loads (gains, residual chunks) hoisted and issued together, chunk waits removed (4 row passes)
# baseline (speedup 1.0000x reference)
; DI float bflo(unsigned w) { return __uint_as_float(w << 16); }
; DI float bfhi(unsigned w) { return __uint_as_float(w & 0xffff0000u); }
; template <bool INB, bool OUTB>
; DI void res_row(const void* hin_, const bf16_t* y, const float* gpost, const float* gnext, void* hout_, bf16_t* xn, int lane) {
;     u32x2 yw[4]; float ss = 0.f;
; #pragma unroll
;     for (int j = 0; j < 4; ++j) { yw[j] = *(const u32x2*)(y + 4 * lane + 256 * j); const float a = bflo(yw[j].x), b = bfhi(yw[j].x), c = bflo(yw[j].y), d = bfhi(yw[j].y); ss += (a * a + b * b) + (c * c + d * d); }
;     const float r1 = rsqrtf(wave_sum(ss) * (1.f / DM) + EPS);
;     f32x4 h[4]; float s2 = 0.f;
; #pragma unroll
;     for (int j = 0; j < 4; ++j) { const int c = 4 * lane + 256 * j; f32x4 hv;
;         if (INB) { const u32x2 hw = *(const u32x2*)((const bf16_t*)hin_ + c); hv = (f32x4){bflo(hw.x), bfhi(hw.x), bflo(hw.y), bfhi(hw.y)}; } else hv = *(const f32x4*)((const float*)hin_ + c);
;     DI void row(int r, int lane) const {
;         const bf16_t* yr = y + (size_t)r * DM; bf16_t* hr = h16 + (size_t)r * DM;
;         if (mode == 0) res_row<false, true>(r < NP ? xp + (size_t)r * DM : xs + (size_t)(r - NP) * DM, yr, gpost, gnext, hr, xnp + (size_t)r * DM, lane);
.LBB0_996:
	v_add_co_u32_e32 v16, vcc, s7, v6
	s_add_i32 s12, s6, 0xffff8000
	s_nop 0
	v_addc_co_u32_e32 v17, vcc, -1, v7, vcc
	global_load_dwordx2 v[24:25], v[16:17], off offset:-1536
	global_load_dwordx2 v[26:27], v[16:17], off offset:-1024
	global_load_dwordx2 v[28:29], v[16:17], off offset:-512
	global_load_dwordx2 v[30:31], v[16:17], off
	s_lshl_b64 s[14:15], s[12:13], 12
	s_add_u32 s12, s10, s14
	s_addc_u32 s14, s11, s15
	s_cmp_lt_i32 s6, 0x8000
	s_cselect_b32 s14, s3, s14
	s_cselect_b32 s12, s2, s12
	v_mov_b32_e32 v20, s12
	v_mov_b32_e32 v21, s14
	v_lshl_add_u64 v[32:33], v[0:1], 2, v[20:21]
	global_load_dwordx4 v[16:19], v[2:3], off
	global_load_dwordx4 v[20:23], v[32:33], off
	s_add_i32 s6, s6, s82
	s_add_u32 s2, s2, s4
	s_addc_u32 s3, s3, s5
	s_cmp_lt_i32 s6, 0x8080
	global_load_dwordx4 v[150:153], v[32:33], off offset:1024
	global_load_dwordx4 v[154:157], v[2:3], off offset:1024
	global_load_dwordx4 v[158:161], v[32:33], off offset:2048
	global_load_dwordx4 v[162:165], v[2:3], off offset:2048
	global_load_dwordx4 v[166:169], v[32:33], off offset:3072
	global_load_dwordx4 v[170:173], v[2:3], off offset:3072
	global_load_dwordx4 v[174:177], v[4:5], off
	global_load_dwordx4 v[178:181], v[4:5], off offset:1024
	global_load_dwordx4 v[182:185], v[4:5], off offset:2048
	global_load_dwordx4 v[186:189], v[4:5], off offset:3072
	s_waitcnt vmcnt(0)
	v_lshlrev_b32_e32 v34, 16, v25
	v_and_b32_e32 v35, 0xffff0000, v25
	v_and_b32_e32 v37, 0xffff0000, v24
	v_and_b32_e32 v25, 0xffff0000, v27
	v_and_b32_e32 v39, 0xffff0000, v26
	v_lshlrev_b32_e32 v36, 16, v24
	v_lshlrev_b32_e32 v24, 16, v27
	v_lshlrev_b32_e32 v38, 16, v26
	v_mov_b32_e32 v44, v37
	v_mov_b32_e32 v45, v35
	v_mov_b32_e32 v48, v39
	v_mov_b32_e32 v49, v25
	v_lshlrev_b32_e32 v26, 16, v29
	v_and_b32_e32 v27, 0xffff0000, v29
	v_lshlrev_b32_e32 v40, 16, v28
	v_and_b32_e32 v41, 0xffff0000, v28
	v_lshlrev_b32_e32 v28, 16, v31
	v_and_b32_e32 v29, 0xffff0000, v31
	v_lshlrev_b32_e32 v42, 16, v30
	v_and_b32_e32 v43, 0xffff0000, v30
	v_mov_b32_e32 v30, v36
	v_mov_b32_e32 v31, v34
	v_mov_b32_e32 v46, v38
	v_mov_b32_e32 v47, v24
	v_pk_mul_f32 v[44:45], v[44:45], v[44:45]
	v_pk_mul_f32 v[48:49], v[48:49], v[48:49]
	v_mul_f32_e32 v50, v27, v27
	v_mul_f32_e32 v52, v41, v41
	v_pk_fma_f32 v[30:31], v[30:31], v[30:31], v[44:45]
	v_pk_fma_f32 v[44:45], v[46:47], v[46:47], v[48:49]
	v_pk_mul_f32 v[54:55], v[28:29], v[28:29]
	v_pk_mul_f32 v[56:57], v[42:43], v[42:43]
	v_pk_fma_f32 v[50:51], v[26:27], v[26:27], v[50:51] op_sel_hi:[1,1,0]
	v_pk_fma_f32 v[52:53], v[40:41], v[40:41], v[52:53] op_sel_hi:[1,1,0]
	v_pk_add_f32 v[30:31], v[30:31], v[30:31] op_sel:[0,1] op_sel_hi:[1,0]
	v_pk_add_f32 v[44:45], v[44:45], v[44:45] op_sel:[0,1] op_sel_hi:[1,0]
	v_mov_b32_e32 v53, v54
	v_mov_b32_e32 v51, v55
	v_mov_b32_e32 v31, v56
	v_mov_b32_e32 v45, v57
	v_pk_add_f32 v[46:47], v[52:53], v[50:51]
	v_pk_add_f32 v[30:31], v[30:31], v[44:45]
	s_nop 0
	v_pk_add_f32 v[30:31], v[30:31], v[46:47]
	s_nop 0
	v_add_f32_e32 v15, v30, v31
	ds_bpermute_b32 v30, v8, v15
	s_waitcnt lgkmcnt(0)
	v_add_f32_e32 v15, v15, v30
	ds_bpermute_b32 v30, v9, v15
	s_waitcnt lgkmcnt(0)
	v_add_f32_e32 v15, v15, v30
	ds_bpermute_b32 v30, v10, v15
	s_waitcnt lgkmcnt(0)
	v_add_f32_e32 v15, v15, v30
	ds_bpermute_b32 v30, v11, v15
	s_waitcnt lgkmcnt(0)
	v_add_f32_e32 v15, v15, v30
	ds_bpermute_b32 v30, v12, v15
	s_waitcnt lgkmcnt(0)
	v_add_f32_e32 v15, v15, v30
	ds_bpermute_b32 v30, v13, v15
	s_waitcnt lgkmcnt(0)
; DI float bflo(unsigned w) { return __uint_as_float(w << 16); }
; DI float bfhi(unsigned w) { return __uint_as_float(w & 0xffff0000u); }
; template <bool INB, bool OUTB>
; DI void res_row(const void* hin_, const bf16_t* y, const float* gpost, const float* gnext, void* hout_, bf16_t* xn, int lane) {
;     ...
;         const f32x4 gp = *(const f32x4*)(gpost + c);
;         h[j][0] = hv[0] + bflo(yw[j].x) * r1 * gp[0]; h[j][1] = hv[1] + bfhi(yw[j].x) * r1 * gp[1]; h[j][2] = hv[2] + bflo(yw[j].y) * r1 * gp[2]; h[j][3] = hv[3] + bfhi(yw[j].y) * r1 * gp[3];
;         if (OUTB) { u32x2 w; w.x = pk2(h[j][0], h[j][1]); w.y = pk2(h[j][2], h[j][3]); *(u32x2*)((bf16_t*)hout_ + c) = w;
;             h[j] = (f32x4){bflo(w.x), bfhi(w.x), bflo(w.y), bfhi(w.y)}; }
;         else *(f32x4*)((float*)hout_ + c) = h[j];
;         s2 += (h[j][0] * h[j][0] + h[j][1] * h[j][1]) + (h[j][2] * h[j][2] + h[j][3] * h[j][3]); }
;     if (xn) {
;         const float r2 = rsqrtf(wave_sum(s2) * (1.f / DM) + EPS);
; #pragma unroll
;         for (int j = 0; j < 4; ++j) { const int c = 4 * lane + 256 * j; const f32x4 gn = *(const f32x4*)(gnext + c); u32x2 w; w.x = pk2(h[j][0] * r2 * gn[0], h[j][1] * r2 * gn[1]); w.y = pk2(h[j][2] * r2 * gn[2], h[j][3] * r2 * gn[3]);
;             *(u32x2*)(xn + c) = w; }
	v_add_f32_e32 v15, v15, v30
	v_fmamk_f32 v15, v15, 0x3a800000, v14
	v_mul_f32_e32 v30, 0x4b800000, v15
	v_cmp_gt_f32_e32 vcc, s8, v15
	s_nop 1
	v_cndmask_b32_e32 v15, v15, v30, vcc
	v_rsq_f32_e32 v15, v15
	s_nop 0
	v_mul_f32_e32 v30, 0x45800000, v15
	v_cndmask_b32_e32 v30, v15, v30, vcc
	v_pk_mul_f32 v[36:37], v[30:31], v[36:37] op_sel_hi:[0,1]
	v_pk_mul_f32 v[34:35], v[30:31], v[34:35] op_sel_hi:[0,1]
	v_pk_fma_f32 v[16:17], v[16:17], v[36:37], v[20:21]
	v_pk_fma_f32 v[18:19], v[18:19], v[34:35], v[22:23]
	v_cvt_pk_bf16_f32 v34, v16, v17
	v_cvt_pk_bf16_f32 v35, v18, v19
	global_store_dwordx2 v[6:7], v[34:35], off offset:-1536
	v_mov_b32_e32 v16, v150
	v_mov_b32_e32 v17, v151
	v_mov_b32_e32 v18, v152
	v_mov_b32_e32 v19, v153
	v_mov_b32_e32 v20, v154
	v_mov_b32_e32 v21, v155
	v_mov_b32_e32 v22, v156
	v_mov_b32_e32 v23, v157
	v_pk_mul_f32 v[36:37], v[30:31], v[38:39] op_sel_hi:[0,1]
	v_pk_mul_f32 v[24:25], v[30:31], v[24:25] op_sel_hi:[0,1]
	v_pk_mul_f32 v[26:27], v[30:31], v[26:27] op_sel_hi:[0,1]
	v_pk_mul_f32 v[28:29], v[30:31], v[28:29] op_sel_hi:[0,1]
	v_and_b32_e32 v39, 0xffff0000, v34
	v_lshlrev_b32_e32 v38, 16, v34
	v_mov_b32_e32 v34, v38
	v_pk_fma_f32 v[16:17], v[20:21], v[36:37], v[16:17]
	v_pk_fma_f32 v[18:19], v[22:23], v[24:25], v[18:19]
	v_cvt_pk_bf16_f32 v24, v16, v17
	v_cvt_pk_bf16_f32 v25, v18, v19
	global_store_dwordx2 v[6:7], v[24:25], off offset:-1024
	v_mov_b32_e32 v16, v158
	v_mov_b32_e32 v17, v159
	v_mov_b32_e32 v18, v160
	v_mov_b32_e32 v19, v161
	v_mov_b32_e32 v20, v162
	v_mov_b32_e32 v21, v163
	v_mov_b32_e32 v22, v164
	v_mov_b32_e32 v23, v165
	v_pk_mul_f32 v[36:37], v[30:31], v[40:41] op_sel_hi:[0,1]
	v_mov_b32_e32 v40, v39
	v_pk_fma_f32 v[16:17], v[20:21], v[36:37], v[16:17]
	v_pk_fma_f32 v[18:19], v[22:23], v[26:27], v[18:19]
	v_cvt_pk_bf16_f32 v26, v16, v17
	v_cvt_pk_bf16_f32 v27, v18, v19
	global_store_dwordx2 v[6:7], v[26:27], off offset:-512
	v_mov_b32_e32 v16, v166
	v_mov_b32_e32 v17, v167
	v_mov_b32_e32 v18, v168
	v_mov_b32_e32 v19, v169
	v_mov_b32_e32 v20, v170
	v_mov_b32_e32 v21, v171
	v_mov_b32_e32 v22, v172
	v_mov_b32_e32 v23, v173
	v_pk_mul_f32 v[36:37], v[30:31], v[42:43] op_sel_hi:[0,1]
	v_and_b32_e32 v31, 0xffff0000, v35
	v_lshlrev_b32_e32 v30, 16, v35
	v_mov_b32_e32 v41, v31
	v_mov_b32_e32 v35, v30
	v_pk_mul_f32 v[40:41], v[40:41], v[40:41]
	v_and_b32_e32 v43, 0xffff0000, v24
	v_pk_fma_f32 v[34:35], v[34:35], v[34:35], v[40:41]
	v_and_b32_e32 v41, 0xffff0000, v25
	v_lshlrev_b32_e32 v40, 16, v25
	v_lshlrev_b32_e32 v42, 16, v24
	v_mov_b32_e32 v44, v43
	v_mov_b32_e32 v45, v41
	v_mov_b32_e32 v24, v42
	v_mov_b32_e32 v25, v40
	v_pk_mul_f32 v[44:45], v[44:45], v[44:45]
	v_pk_add_f32 v[34:35], v[34:35], v[34:35] op_sel_hi:[0,1]
	v_pk_fma_f32 v[24:25], v[24:25], v[24:25], v[44:45]
	v_add_co_u32_e32 v32, vcc, s9, v6
	v_pk_fma_f32 v[16:17], v[20:21], v[36:37], v[16:17]
	v_pk_fma_f32 v[18:19], v[22:23], v[28:29], v[18:19]
	v_cvt_pk_bf16_f32 v20, v16, v17
	v_cvt_pk_bf16_f32 v21, v18, v19
	global_store_dwordx2 v[6:7], v[20:21], off
	v_mov_b32_e32 v16, v174
	v_mov_b32_e32 v17, v175
	v_mov_b32_e32 v18, v176
	v_mov_b32_e32 v19, v177
	v_pk_add_f32 v[22:23], v[24:25], v[24:25] op_sel_hi:[0,1]
	v_lshlrev_b32_e32 v24, 16, v27
	v_lshlrev_b32_e32 v28, 16, v26
	v_and_b32_e32 v25, 0xffff0000, v27
	v_and_b32_e32 v29, 0xffff0000, v26
	v_mul_f32_e32 v22, v24, v24
	v_mul_f32_e32 v26, v28, v28
	v_lshlrev_b32_e32 v44, 16, v21
	v_and_b32_e32 v45, 0xffff0000, v21
	v_lshlrev_b32_e32 v46, 16, v20
	v_and_b32_e32 v47, 0xffff0000, v20
	v_pk_fma_f32 v[36:37], v[24:25], v[24:25], v[22:23] op_sel_hi:[1,1,0]
	v_pk_fma_f32 v[26:27], v[28:29], v[28:29], v[26:27] op_sel_hi:[1,1,0]
	v_pk_mul_f32 v[20:21], v[44:45], v[44:45]
	v_pk_mul_f32 v[48:49], v[46:47], v[46:47]
	v_mov_b32_e32 v34, v20
	v_mov_b32_e32 v22, v21
	v_mov_b32_e32 v26, v48
	v_mov_b32_e32 v36, v49
	v_pk_add_f32 v[20:21], v[34:35], v[22:23]
	v_pk_add_f32 v[22:23], v[26:27], v[36:37]
	v_addc_co_u32_e32 v33, vcc, -1, v7, vcc
	v_pk_add_f32 v[20:21], v[22:23], v[20:21]
	v_lshl_add_u64 v[6:7], v[6:7], 0, s[0:1]
	v_add_f32_e32 v15, v20, v21
	ds_bpermute_b32 v20, v8, v15
	s_waitcnt lgkmcnt(0)
	v_add_f32_e32 v15, v15, v20
	ds_bpermute_b32 v20, v9, v15
	s_waitcnt lgkmcnt(0)
	v_add_f32_e32 v15, v15, v20
	ds_bpermute_b32 v20, v10, v15
	s_waitcnt lgkmcnt(0)
	v_add_f32_e32 v15, v15, v20
	ds_bpermute_b32 v20, v11, v15
	s_waitcnt lgkmcnt(0)
	v_add_f32_e32 v15, v15, v20
	ds_bpermute_b32 v20, v12, v15
	s_waitcnt lgkmcnt(0)
	v_add_f32_e32 v15, v15, v20
	ds_bpermute_b32 v20, v13, v15
	s_waitcnt lgkmcnt(0)
	v_add_f32_e32 v15, v15, v20
	v_fmamk_f32 v15, v15, 0x3a800000, v14
	v_mul_f32_e32 v20, 0x4b800000, v15
	v_cmp_gt_f32_e32 vcc, s8, v15
	s_nop 1
	v_cndmask_b32_e32 v15, v15, v20, vcc
	v_rsq_f32_e32 v15, v15
	s_nop 0
	v_mul_f32_e32 v20, 0x45800000, v15
	v_cndmask_b32_e32 v20, v15, v20, vcc
	v_pk_mul_f32 v[22:23], v[20:21], v[38:39] op_sel_hi:[0,1]
	v_pk_mul_f32 v[26:27], v[20:21], v[30:31] op_sel_hi:[0,1]
	v_pk_mul_f32 v[24:25], v[20:21], v[24:25] op_sel_hi:[0,1]
	v_pk_mul_f32 v[16:17], v[16:17], v[22:23]
	v_pk_mul_f32 v[18:19], v[18:19], v[26:27]
	v_cvt_pk_bf16_f32 v16, v16, v17
	v_cvt_pk_bf16_f32 v17, v18, v19
	global_store_dwordx2 v[32:33], v[16:17], off offset:-1536
	v_mov_b32_e32 v16, v178
	v_mov_b32_e32 v17, v179
	v_mov_b32_e32 v18, v180
	v_mov_b32_e32 v19, v181
	v_pk_mul_f32 v[22:23], v[20:21], v[42:43] op_sel_hi:[0,1]
	v_pk_mul_f32 v[26:27], v[20:21], v[40:41] op_sel_hi:[0,1]
	v_pk_mul_f32 v[16:17], v[16:17], v[22:23]
	v_pk_mul_f32 v[18:19], v[18:19], v[26:27]
	v_cvt_pk_bf16_f32 v16, v16, v17
	v_cvt_pk_bf16_f32 v17, v18, v19
	global_store_dwordx2 v[32:33], v[16:17], off offset:-1024
	v_mov_b32_e32 v16, v182
	v_mov_b32_e32 v17, v183
	v_mov_b32_e32 v18, v184
	v_mov_b32_e32 v19, v185
	v_pk_mul_f32 v[22:23], v[20:21], v[28:29] op_sel_hi:[0,1]
	v_pk_mul_f32 v[16:17], v[16:17], v[22:23]
	v_pk_mul_f32 v[18:19], v[18:19], v[24:25]
	v_cvt_pk_bf16_f32 v16, v16, v17
	v_cvt_pk_bf16_f32 v17, v18, v19
	global_store_dwordx2 v[32:33], v[16:17], off offset:-512
	v_mov_b32_e32 v16, v186
	v_mov_b32_e32 v17, v187
	v_mov_b32_e32 v18, v188
	v_mov_b32_e32 v19, v189
	v_pk_mul_f32 v[22:23], v[20:21], v[46:47] op_sel_hi:[0,1]
	v_pk_mul_f32 v[20:21], v[20:21], v[44:45] op_sel_hi:[0,1]
	v_pk_mul_f32 v[16:17], v[16:17], v[22:23]
	v_pk_mul_f32 v[18:19], v[18:19], v[20:21]
	v_cvt_pk_bf16_f32 v16, v16, v17
	v_cvt_pk_bf16_f32 v17, v18, v19
	global_store_dwordx2 v[32:33], v[16:17], off
	s_cbranch_scc1 .LBB0_996

; DI float bflo(unsigned w) { return __uint_as_float(w << 16); }
; DI float bfhi(unsigned w) { return __uint_as_float(w & 0xffff0000u); }
; template <bool INB, bool OUTB>
; DI void res_row(const void* hin_, const bf16_t* y, const float* gpost, const float* gnext, void* hout_, bf16_t* xn, int lane) {
;     u32x2 yw[4]; float ss = 0.f;
; #pragma unroll
;     for (int j = 0; j < 4; ++j) { yw[j] = *(const u32x2*)(y + 4 * lane + 256 * j); const float a = bflo(yw[j].x), b = bfhi(yw[j].x), c = bflo(yw[j].y), d = bfhi(yw[j].y); ss += (a * a + b * b) + (c * c + d * d); }
;     const float r1 = rsqrtf(wave_sum(ss) * (1.f / DM) + EPS);
;     f32x4 h[4]; float s2 = 0.f;
; #pragma unroll
;     for (int j = 0; j < 4; ++j) { const int c = 4 * lane + 256 * j; f32x4 hv;
;         if (INB) { const u32x2 hw = *(const u32x2*)((const bf16_t*)hin_ + c); hv = (f32x4){bflo(hw.x), bfhi(hw.x), bflo(hw.y), bfhi(hw.y)}; } else hv = *(const f32x4*)((const float*)hin_ + c);
;     DI void row(int r, int lane) const {
;         const bf16_t* yr = y + (size_t)r * DM; bf16_t* hr = h16 + (size_t)r * DM;
;         if (mode == 0) res_row<false, true>(r < NP ? xp + (size_t)r * DM : xs + (size_t)(r - NP) * DM, yr, gpost, gnext, hr, xnp + (size_t)r * DM, lane);
;         else if (mode == 1) res_row<true, true>(hr, yr, gpost, gnext, hr, xnp + (size_t)r * DM, lane);
.LBB0_1188:
	v_add_co_u32_e32 v18, vcc, 0xfbf00000, v4
	s_add_i32 s6, s6, s82
	s_nop 0
	v_addc_co_u32_e32 v19, vcc, -1, v5, vcc
	global_load_dwordx2 v[20:21], v[18:19], off offset:-1536
	global_load_dwordx2 v[22:23], v[18:19], off offset:-1024
	global_load_dwordx2 v[24:25], v[18:19], off offset:-512
	global_load_dwordx2 v[26:27], v[18:19], off
	global_load_dwordx2 v[28:29], v[4:5], off offset:-1536
	global_load_dwordx4 v[14:17], v[0:1], off
	global_load_dwordx2 v[30:31], v[4:5], off offset:-1024
	global_load_dwordx2 v[32:33], v[4:5], off offset:-512
	global_load_dwordx2 v[34:35], v[4:5], off
	s_cmp_lt_i32 s6, 0x8080
	global_load_dwordx4 v[150:153], v[0:1], off offset:1024
	global_load_dwordx4 v[154:157], v[0:1], off offset:2048
	global_load_dwordx4 v[158:161], v[0:1], off offset:3072
	global_load_dwordx4 v[162:165], v[2:3], off
	global_load_dwordx4 v[166:169], v[2:3], off offset:1024
	global_load_dwordx4 v[170:173], v[2:3], off offset:2048
	global_load_dwordx4 v[174:177], v[2:3], off offset:3072
	s_waitcnt vmcnt(0)
	v_and_b32_e32 v39, 0xffff0000, v20
	v_and_b32_e32 v41, 0xffff0000, v22
	v_lshlrev_b32_e32 v38, 16, v20
	v_lshlrev_b32_e32 v20, 16, v23
	v_lshlrev_b32_e32 v18, 16, v29
	v_and_b32_e32 v19, 0xffff0000, v29
	v_lshlrev_b32_e32 v36, 16, v28
	v_and_b32_e32 v37, 0xffff0000, v28
	v_lshlrev_b32_e32 v28, 16, v21
	v_and_b32_e32 v29, 0xffff0000, v21
	v_and_b32_e32 v21, 0xffff0000, v23
	v_lshlrev_b32_e32 v40, 16, v22
	v_mov_b32_e32 v46, v39
	v_mov_b32_e32 v47, v29
	v_mov_b32_e32 v50, v41
	v_mov_b32_e32 v51, v21
	v_lshlrev_b32_e32 v22, 16, v25
	v_and_b32_e32 v23, 0xffff0000, v25
	v_lshlrev_b32_e32 v42, 16, v24
	v_and_b32_e32 v43, 0xffff0000, v24
	v_lshlrev_b32_e32 v24, 16, v27
	v_and_b32_e32 v25, 0xffff0000, v27
	v_lshlrev_b32_e32 v44, 16, v26
	v_and_b32_e32 v45, 0xffff0000, v26
	v_mov_b32_e32 v26, v38
	v_mov_b32_e32 v27, v28
	v_mov_b32_e32 v48, v40
	v_mov_b32_e32 v49, v20
	v_pk_mul_f32 v[46:47], v[46:47], v[46:47]
	v_pk_mul_f32 v[50:51], v[50:51], v[50:51]
	v_mul_f32_e32 v52, v23, v23
	v_mul_f32_e32 v54, v43, v43
	v_pk_fma_f32 v[26:27], v[26:27], v[26:27], v[46:47]
	v_pk_fma_f32 v[46:47], v[48:49], v[48:49], v[50:51]
	v_pk_mul_f32 v[56:57], v[24:25], v[24:25]
	v_pk_mul_f32 v[58:59], v[44:45], v[44:45]
	v_pk_fma_f32 v[52:53], v[22:23], v[22:23], v[52:53] op_sel_hi:[1,1,0]
	v_pk_fma_f32 v[54:55], v[42:43], v[42:43], v[54:55] op_sel_hi:[1,1,0]
	v_pk_add_f32 v[26:27], v[26:27], v[26:27] op_sel:[0,1] op_sel_hi:[1,0]
	v_pk_add_f32 v[46:47], v[46:47], v[46:47] op_sel:[0,1] op_sel_hi:[1,0]
	v_mov_b32_e32 v55, v56
	v_mov_b32_e32 v53, v57
	v_mov_b32_e32 v27, v58
	v_mov_b32_e32 v47, v59
	v_pk_add_f32 v[48:49], v[54:55], v[52:53]
	v_pk_add_f32 v[26:27], v[26:27], v[46:47]
	s_nop 0
	v_pk_add_f32 v[26:27], v[26:27], v[48:49]
	s_nop 0
	v_add_f32_e32 v13, v26, v27
	ds_bpermute_b32 v26, v6, v13
	s_waitcnt lgkmcnt(0)
	v_add_f32_e32 v13, v13, v26
	ds_bpermute_b32 v26, v7, v13
	s_waitcnt lgkmcnt(0)
	v_add_f32_e32 v13, v13, v26
	ds_bpermute_b32 v26, v8, v13
	s_waitcnt lgkmcnt(0)
	v_add_f32_e32 v13, v13, v26
	ds_bpermute_b32 v26, v9, v13
	s_waitcnt lgkmcnt(0)
	v_add_f32_e32 v13, v13, v26
	ds_bpermute_b32 v26, v10, v13
	s_waitcnt lgkmcnt(0)
	v_add_f32_e32 v13, v13, v26
	ds_bpermute_b32 v26, v11, v13
	s_waitcnt lgkmcnt(0)
; DI float bflo(unsigned w) { return __uint_as_float(w << 16); }
; DI float bfhi(unsigned w) { return __uint_as_float(w & 0xffff0000u); }
; template <bool INB, bool OUTB>
; DI void res_row(const void* hin_, const bf16_t* y, const float* gpost, const float* gnext, void* hout_, bf16_t* xn, int lane) {
;     ...
;         const f32x4 gp = *(const f32x4*)(gpost + c);
;         h[j][0] = hv[0] + bflo(yw[j].x) * r1 * gp[0]; h[j][1] = hv[1] + bfhi(yw[j].x) * r1 * gp[1]; h[j][2] = hv[2] + bflo(yw[j].y) * r1 * gp[2]; h[j][3] = hv[3] + bfhi(yw[j].y) * r1 * gp[3];
;         if (OUTB) { u32x2 w; w.x = pk2(h[j][0], h[j][1]); w.y = pk2(h[j][2], h[j][3]); *(u32x2*)((bf16_t*)hout_ + c) = w;
;             h[j] = (f32x4){bflo(w.x), bfhi(w.x), bflo(w.y), bfhi(w.y)}; }
;         else *(f32x4*)((float*)hout_ + c) = h[j];
;         s2 += (h[j][0] * h[j][0] + h[j][1] * h[j][1]) + (h[j][2] * h[j][2] + h[j][3] * h[j][3]); }
;     if (xn) {
;         const float r2 = rsqrtf(wave_sum(s2) * (1.f / DM) + EPS);
; #pragma unroll
;         for (int j = 0; j < 4; ++j) { const int c = 4 * lane + 256 * j; const f32x4 gn = *(const f32x4*)(gnext + c); u32x2 w; w.x = pk2(h[j][0] * r2 * gn[0], h[j][1] * r2 * gn[1]); w.y = pk2(h[j][2] * r2 * gn[2], h[j][3] * r2 * gn[3]);
;             *(u32x2*)(xn + c) = w; }
	v_add_f32_e32 v13, v13, v26
	v_fmamk_f32 v13, v13, 0x3a800000, v12
	v_mul_f32_e32 v26, 0x4b800000, v13
	v_cmp_gt_f32_e32 vcc, s2, v13
	s_nop 1
	v_cndmask_b32_e32 v13, v13, v26, vcc
	v_rsq_f32_e32 v13, v13
	s_nop 0
	v_mul_f32_e32 v26, 0x45800000, v13
	v_cndmask_b32_e32 v26, v13, v26, vcc
	v_pk_mul_f32 v[38:39], v[26:27], v[38:39] op_sel_hi:[0,1]
	v_pk_mul_f32 v[28:29], v[26:27], v[28:29] op_sel_hi:[0,1]
	v_pk_fma_f32 v[14:15], v[14:15], v[38:39], v[36:37]
	v_pk_fma_f32 v[16:17], v[16:17], v[28:29], v[18:19]
	v_cvt_pk_bf16_f32 v18, v14, v15
	v_cvt_pk_bf16_f32 v19, v16, v17
	global_store_dwordx2 v[4:5], v[18:19], off offset:-1536
	v_mov_b32_e32 v14, v150
	v_mov_b32_e32 v15, v151
	v_mov_b32_e32 v16, v152
	v_mov_b32_e32 v17, v153
	v_lshlrev_b32_e32 v28, 16, v31
	v_and_b32_e32 v29, 0xffff0000, v31
	v_lshlrev_b32_e32 v36, 16, v30
	v_and_b32_e32 v37, 0xffff0000, v30
	v_pk_mul_f32 v[30:31], v[26:27], v[40:41] op_sel_hi:[0,1]
	v_pk_mul_f32 v[20:21], v[26:27], v[20:21] op_sel_hi:[0,1]
	v_pk_mul_f32 v[22:23], v[26:27], v[22:23] op_sel_hi:[0,1]
	v_pk_mul_f32 v[24:25], v[26:27], v[24:25] op_sel_hi:[0,1]
	v_pk_fma_f32 v[14:15], v[14:15], v[30:31], v[36:37]
	v_pk_fma_f32 v[16:17], v[16:17], v[20:21], v[28:29]
	v_cvt_pk_bf16_f32 v20, v14, v15
	v_cvt_pk_bf16_f32 v21, v16, v17
	global_store_dwordx2 v[4:5], v[20:21], off offset:-1024
	v_mov_b32_e32 v14, v154
	v_mov_b32_e32 v15, v155
	v_mov_b32_e32 v16, v156
	v_mov_b32_e32 v17, v157
	v_lshlrev_b32_e32 v28, 16, v33
	v_and_b32_e32 v29, 0xffff0000, v33
	v_lshlrev_b32_e32 v30, 16, v32
	v_and_b32_e32 v31, 0xffff0000, v32
	v_pk_mul_f32 v[32:33], v[26:27], v[42:43] op_sel_hi:[0,1]
	v_and_b32_e32 v37, 0xffff0000, v18
	v_lshlrev_b32_e32 v36, 16, v18
	v_mov_b32_e32 v38, v37
	v_mov_b32_e32 v18, v36
	v_and_b32_e32 v41, 0xffff0000, v20
	v_lshlrev_b32_e32 v40, 16, v20
	v_mov_b32_e32 v42, v41
	v_mov_b32_e32 v20, v40
	v_pk_fma_f32 v[14:15], v[14:15], v[32:33], v[30:31]
	v_pk_fma_f32 v[16:17], v[16:17], v[22:23], v[28:29]
	v_cvt_pk_bf16_f32 v22, v14, v15
	v_cvt_pk_bf16_f32 v23, v16, v17
	global_store_dwordx2 v[4:5], v[22:23], off offset:-512
	v_mov_b32_e32 v14, v158
	v_mov_b32_e32 v15, v159
	v_mov_b32_e32 v16, v160
	v_mov_b32_e32 v17, v161
	v_lshlrev_b32_e32 v30, 16, v35
	v_and_b32_e32 v31, 0xffff0000, v35
	v_lshlrev_b32_e32 v32, 16, v34
	v_and_b32_e32 v33, 0xffff0000, v34
	v_pk_mul_f32 v[34:35], v[26:27], v[44:45] op_sel_hi:[0,1]
	v_and_b32_e32 v27, 0xffff0000, v19
	v_lshlrev_b32_e32 v26, 16, v19
	v_mov_b32_e32 v39, v27
	v_mov_b32_e32 v19, v26
	v_pk_mul_f32 v[38:39], v[38:39], v[38:39]
	v_add_co_u32_e32 v28, vcc, s3, v4
	v_pk_fma_f32 v[18:19], v[18:19], v[18:19], v[38:39]
	v_and_b32_e32 v39, 0xffff0000, v21
	v_lshlrev_b32_e32 v38, 16, v21
	v_mov_b32_e32 v43, v39
	v_mov_b32_e32 v21, v38
	v_pk_mul_f32 v[42:43], v[42:43], v[42:43]
	v_pk_add_f32 v[18:19], v[18:19], v[18:19] op_sel_hi:[0,1]
	v_pk_fma_f32 v[20:21], v[20:21], v[20:21], v[42:43]
	v_addc_co_u32_e32 v29, vcc, -1, v5, vcc
	v_pk_add_f32 v[20:21], v[20:21], v[20:21] op_sel_hi:[0,1]
	v_pk_fma_f32 v[14:15], v[14:15], v[34:35], v[32:33]
	v_pk_fma_f32 v[16:17], v[16:17], v[24:25], v[30:31]
	v_cvt_pk_bf16_f32 v24, v14, v15
	v_cvt_pk_bf16_f32 v25, v16, v17
	global_store_dwordx2 v[4:5], v[24:25], off
	v_mov_b32_e32 v14, v162
	v_mov_b32_e32 v15, v163
	v_mov_b32_e32 v16, v164
	v_mov_b32_e32 v17, v165
	v_lshlrev_b32_e32 v30, 16, v23
	v_lshlrev_b32_e32 v32, 16, v22
	v_and_b32_e32 v31, 0xffff0000, v23
	v_and_b32_e32 v33, 0xffff0000, v22
	v_mul_f32_e32 v18, v30, v30
	v_mul_f32_e32 v20, v32, v32
	v_lshlrev_b32_e32 v42, 16, v25
	v_and_b32_e32 v43, 0xffff0000, v25
	v_lshlrev_b32_e32 v44, 16, v24
	v_and_b32_e32 v45, 0xffff0000, v24
	v_pk_fma_f32 v[22:23], v[30:31], v[30:31], v[18:19] op_sel_hi:[1,1,0]
	v_pk_fma_f32 v[34:35], v[32:33], v[32:33], v[20:21] op_sel_hi:[1,1,0]
	v_pk_mul_f32 v[24:25], v[42:43], v[42:43]
	v_pk_mul_f32 v[46:47], v[44:45], v[44:45]
	v_mov_b32_e32 v18, v24
	v_mov_b32_e32 v20, v25
	v_mov_b32_e32 v34, v46
	v_mov_b32_e32 v22, v47
	v_pk_add_f32 v[18:19], v[18:19], v[20:21]
	v_pk_add_f32 v[20:21], v[34:35], v[22:23]
	v_lshl_add_u64 v[4:5], v[4:5], 0, s[0:1]
	v_pk_add_f32 v[18:19], v[20:21], v[18:19]
	s_nop 0
	v_add_f32_e32 v13, v18, v19
	ds_bpermute_b32 v18, v6, v13
	s_waitcnt lgkmcnt(0)
	v_add_f32_e32 v13, v13, v18
	ds_bpermute_b32 v18, v7, v13
	s_waitcnt lgkmcnt(0)
	v_add_f32_e32 v13, v13, v18
	ds_bpermute_b32 v18, v8, v13
	s_waitcnt lgkmcnt(0)
	v_add_f32_e32 v13, v13, v18
	ds_bpermute_b32 v18, v9, v13
	s_waitcnt lgkmcnt(0)
	v_add_f32_e32 v13, v13, v18
	ds_bpermute_b32 v18, v10, v13
	s_waitcnt lgkmcnt(0)
	v_add_f32_e32 v13, v13, v18
	ds_bpermute_b32 v18, v11, v13
	s_waitcnt lgkmcnt(0)
	v_add_f32_e32 v13, v13, v18
	v_fmamk_f32 v13, v13, 0x3a800000, v12
	v_mul_f32_e32 v18, 0x4b800000, v13
	v_cmp_gt_f32_e32 vcc, s2, v13
	s_nop 1
	v_cndmask_b32_e32 v13, v13, v18, vcc
	v_rsq_f32_e32 v13, v13
	s_nop 0
	v_mul_f32_e32 v18, 0x45800000, v13
	v_cndmask_b32_e32 v18, v13, v18, vcc
	v_pk_mul_f32 v[20:21], v[18:19], v[36:37] op_sel_hi:[0,1]
	v_pk_mul_f32 v[22:23], v[18:19], v[26:27] op_sel_hi:[0,1]
	v_pk_mul_f32 v[14:15], v[14:15], v[20:21]
	v_pk_mul_f32 v[16:17], v[16:17], v[22:23]
	v_cvt_pk_bf16_f32 v14, v14, v15
	v_cvt_pk_bf16_f32 v15, v16, v17
	global_store_dwordx2 v[28:29], v[14:15], off offset:-1536
	v_mov_b32_e32 v14, v166
	v_mov_b32_e32 v15, v167
	v_mov_b32_e32 v16, v168
	v_mov_b32_e32 v17, v169
	v_pk_mul_f32 v[20:21], v[18:19], v[40:41] op_sel_hi:[0,1]
	v_pk_mul_f32 v[22:23], v[18:19], v[38:39] op_sel_hi:[0,1]
	v_pk_mul_f32 v[14:15], v[14:15], v[20:21]
	v_pk_mul_f32 v[16:17], v[16:17], v[22:23]
	v_cvt_pk_bf16_f32 v14, v14, v15
	v_cvt_pk_bf16_f32 v15, v16, v17
	global_store_dwordx2 v[28:29], v[14:15], off offset:-1024
	v_mov_b32_e32 v14, v170
	v_mov_b32_e32 v15, v171
	v_mov_b32_e32 v16, v172
	v_mov_b32_e32 v17, v173
	v_pk_mul_f32 v[20:21], v[18:19], v[32:33] op_sel_hi:[0,1]
	v_pk_mul_f32 v[22:23], v[18:19], v[30:31] op_sel_hi:[0,1]
	v_pk_mul_f32 v[14:15], v[14:15], v[20:21]
	v_pk_mul_f32 v[16:17], v[16:17], v[22:23]
	v_cvt_pk_bf16_f32 v14, v14, v15
	v_cvt_pk_bf16_f32 v15, v16, v17
	global_store_dwordx2 v[28:29], v[14:15], off offset:-512
	v_mov_b32_e32 v14, v174
	v_mov_b32_e32 v15, v175
	v_mov_b32_e32 v16, v176
	v_mov_b32_e32 v17, v177
	v_pk_mul_f32 v[20:21], v[18:19], v[44:45] op_sel_hi:[0,1]
	v_pk_mul_f32 v[18:19], v[18:19], v[42:43] op_sel_hi:[0,1]
	v_pk_mul_f32 v[14:15], v[14:15], v[20:21]
	v_pk_mul_f32 v[16:17], v[16:17], v[18:19]
	v_cvt_pk_bf16_f32 v14, v14, v15
	v_cvt_pk_bf16_f32 v15, v16, v17
	global_store_dwordx2 v[28:29], v[14:15], off
	s_cbranch_scc1 .LBB0_1188

; DI float bflo(unsigned w) { return __uint_as_float(w << 16); }
; DI float bfhi(unsigned w) { return __uint_as_float(w & 0xffff0000u); }
; template <bool INB, bool OUTB>
; DI void res_row(const void* hin_, const bf16_t* y, const float* gpost, const float* gnext, void* hout_, bf16_t* xn, int lane) {
;     u32x2 yw[4]; float ss = 0.f;
; #pragma unroll
;     for (int j = 0; j < 4; ++j) { yw[j] = *(const u32x2*)(y + 4 * lane + 256 * j); const float a = bflo(yw[j].x), b = bfhi(yw[j].x), c = bflo(yw[j].y), d = bfhi(yw[j].y); ss += (a * a + b * b) + (c * c + d * d); }
;     const float r1 = rsqrtf(wave_sum(ss) * (1.f / DM) + EPS);
;     f32x4 h[4]; float s2 = 0.f;
; #pragma unroll
;     for (int j = 0; j < 4; ++j) { const int c = 4 * lane + 256 * j; f32x4 hv;
;         if (INB) { const u32x2 hw = *(const u32x2*)((const bf16_t*)hin_ + c); hv = (f32x4){bflo(hw.x), bfhi(hw.x), bflo(hw.y), bfhi(hw.y)}; } else hv = *(const f32x4*)((const float*)hin_ + c);
;         const f32x4 gp = *(const f32x4*)(gpost + c);
;         h[j][0] = hv[0] + bflo(yw[j].x) * r1 * gp[0]; h[j][1] = hv[1] + bfhi(yw[j].x) * r1 * gp[1]; h[j][2] = hv[2] + bflo(yw[j].y) * r1 * gp[2]; h[j][3] = hv[3] + bfhi(yw[j].y) * r1 * gp[3];
;         if (OUTB) { u32x2 w; w.x = pk2(h[j][0], h[j][1]); w.y = pk2(h[j][2], h[j][3]); *(u32x2*)((bf16_t*)hout_ + c) = w;
;             h[j] = (f32x4){bflo(w.x), bfhi(w.x), bflo(w.y), bfhi(w.y)}; }
;         else *(f32x4*)((float*)hout_ + c) = h[j];
;     DI void row(int r, int lane) const {
;     ...
;         else res_row<true, false>(hr, yr, gpost, gnext, r < NP ? out + O_YP + (size_t)r * DM : out + O_YS + (size_t)(r - NP) * DM, nullptr, lane);
.LBB0_1923:
	s_nop 0
	v_add_co_u32_e32 v14, vcc, s11, v4
	s_add_i32 s6, s2, 0xffff8000
	s_nop 0
	v_addc_co_u32_e32 v15, vcc, -1, v5, vcc
	global_load_dwordx2 v[18:19], v[14:15], off offset:-1536
	global_load_dwordx2 v[20:21], v[14:15], off offset:-1024
	global_load_dwordx2 v[22:23], v[14:15], off offset:-512
	global_load_dwordx2 v[24:25], v[14:15], off
	global_load_dwordx2 v[26:27], v[4:5], off offset:-1536
	s_lshl_b64 s[14:15], s[6:7], 12
	global_load_dwordx4 v[14:17], v[2:3], off
	s_add_u32 s6, s8, s14
	s_addc_u32 s13, s9, s15
	s_cmp_lt_i32 s2, 0x8000
	s_cselect_b32 s13, s10, s13
	s_cselect_b32 s6, s3, s6
	v_mov_b32_e32 v28, s6
	v_mov_b32_e32 v29, s13
	v_lshl_add_u64 v[28:29], v[0:1], 2, v[28:29]
	s_add_i32 s2, s2, s82
	s_add_u32 s3, s3, s0
	s_addc_u32 s10, s10, s1
	s_cmp_lt_i32 s2, 0x8080
	global_load_dwordx2 v[150:151], v[4:5], off offset:-1024
	global_load_dwordx4 v[152:155], v[2:3], off offset:1024
	global_load_dwordx2 v[156:157], v[4:5], off offset:-512
	global_load_dwordx4 v[158:161], v[2:3], off offset:2048
	global_load_dwordx2 v[162:163], v[4:5], off
	global_load_dwordx4 v[164:167], v[2:3], off offset:3072
	s_waitcnt vmcnt(0)
	v_lshlrev_b32_e32 v32, 16, v18
	v_and_b32_e32 v33, 0xffff0000, v18
	v_lshlrev_b32_e32 v18, 16, v19
	v_and_b32_e32 v19, 0xffff0000, v19
	v_lshlrev_b32_e32 v34, 16, v20
	v_and_b32_e32 v35, 0xffff0000, v20
	v_lshlrev_b32_e32 v20, 16, v21
	v_and_b32_e32 v21, 0xffff0000, v21
	v_mov_b32_e32 v42, v33
	v_mov_b32_e32 v43, v19
	v_mov_b32_e32 v46, v35
	v_mov_b32_e32 v47, v21
	v_lshlrev_b32_e32 v36, 16, v22
	v_and_b32_e32 v37, 0xffff0000, v22
	v_lshlrev_b32_e32 v22, 16, v23
	v_and_b32_e32 v23, 0xffff0000, v23
	v_mov_b32_e32 v40, v32
	v_mov_b32_e32 v41, v18
	v_mov_b32_e32 v44, v34
	v_mov_b32_e32 v45, v20
	v_pk_mul_f32 v[42:43], v[42:43], v[42:43]
	v_pk_mul_f32 v[46:47], v[46:47], v[46:47]
	v_lshlrev_b32_e32 v38, 16, v24
	v_and_b32_e32 v39, 0xffff0000, v24
	v_lshlrev_b32_e32 v24, 16, v25
	v_and_b32_e32 v25, 0xffff0000, v25
	v_mul_f32_e32 v48, v37, v37
	v_mul_f32_e32 v50, v23, v23
	v_pk_fma_f32 v[40:41], v[40:41], v[40:41], v[42:43]
	v_pk_fma_f32 v[42:43], v[44:45], v[44:45], v[46:47]
	v_pk_mul_f32 v[52:53], v[38:39], v[38:39]
	v_pk_mul_f32 v[54:55], v[24:25], v[24:25]
	v_pk_fma_f32 v[48:49], v[36:37], v[36:37], v[48:49] op_sel_hi:[1,1,0]
	v_pk_fma_f32 v[50:51], v[22:23], v[22:23], v[50:51] op_sel_hi:[1,1,0]
	v_pk_add_f32 v[40:41], v[40:41], v[40:41] op_sel:[0,1] op_sel_hi:[1,0]
	v_pk_add_f32 v[42:43], v[42:43], v[42:43] op_sel:[0,1] op_sel_hi:[1,0]
	v_mov_b32_e32 v49, v54
	v_mov_b32_e32 v51, v55
	v_mov_b32_e32 v41, v52
	v_mov_b32_e32 v43, v53
	v_pk_add_f32 v[44:45], v[48:49], v[50:51]
	v_pk_add_f32 v[40:41], v[40:41], v[42:43]
	v_lshlrev_b32_e32 v30, 16, v26
	v_pk_add_f32 v[40:41], v[40:41], v[44:45]
	v_and_b32_e32 v31, 0xffff0000, v26
	v_add_f32_e32 v13, v40, v41
	ds_bpermute_b32 v40, v6, v13
	v_lshlrev_b32_e32 v26, 16, v27
	v_and_b32_e32 v27, 0xffff0000, v27
	s_waitcnt lgkmcnt(0)
	v_add_f32_e32 v13, v13, v40
	ds_bpermute_b32 v40, v7, v13
	s_waitcnt lgkmcnt(0)
	v_add_f32_e32 v13, v13, v40
	ds_bpermute_b32 v40, v8, v13
	s_waitcnt lgkmcnt(0)
	v_add_f32_e32 v13, v13, v40
	ds_bpermute_b32 v40, v9, v13
	s_waitcnt lgkmcnt(0)
	v_add_f32_e32 v13, v13, v40
	ds_bpermute_b32 v40, v10, v13
	s_waitcnt lgkmcnt(0)
	v_add_f32_e32 v13, v13, v40
	ds_bpermute_b32 v40, v11, v13
	s_waitcnt lgkmcnt(0)
	v_add_f32_e32 v13, v13, v40
	v_fmamk_f32 v13, v13, 0x3a800000, v12
	v_mul_f32_e32 v40, 0x4b800000, v13
	v_cmp_gt_f32_e32 vcc, s12, v13
	s_nop 1
	v_cndmask_b32_e32 v13, v13, v40, vcc
	v_rsq_f32_e32 v13, v13
	s_nop 0
	v_mul_f32_e32 v40, 0x45800000, v13
	v_cndmask_b32_e32 v40, v13, v40, vcc
	v_pk_mul_f32 v[32:33], v[40:41], v[32:33] op_sel_hi:[0,1]
	v_pk_mul_f32 v[18:19], v[40:41], v[18:19] op_sel_hi:[0,1]
	v_pk_fma_f32 v[14:15], v[14:15], v[32:33], v[30:31]
	v_pk_fma_f32 v[16:17], v[16:17], v[18:19], v[26:27]
	global_store_dwordx4 v[28:29], v[14:17], off
	v_mov_b32_e32 v18, v150
	v_mov_b32_e32 v19, v151
	s_nop 0
	v_mov_b32_e32 v14, v152
	v_mov_b32_e32 v15, v153
	v_mov_b32_e32 v16, v154
	v_mov_b32_e32 v17, v155
	v_pk_mul_f32 v[26:27], v[40:41], v[34:35] op_sel_hi:[0,1]
	v_pk_mul_f32 v[20:21], v[40:41], v[20:21] op_sel_hi:[0,1]
	v_pk_mul_f32 v[22:23], v[40:41], v[22:23] op_sel_hi:[0,1]
	s_waitcnt vmcnt(1)
	v_lshlrev_b32_e32 v30, 16, v18
	v_and_b32_e32 v31, 0xffff0000, v18
	v_lshlrev_b32_e32 v18, 16, v19
	v_and_b32_e32 v19, 0xffff0000, v19
	v_pk_fma_f32 v[14:15], v[14:15], v[26:27], v[30:31]
	v_pk_fma_f32 v[16:17], v[16:17], v[20:21], v[18:19]
	global_store_dwordx4 v[28:29], v[14:17], off offset:1024
	v_mov_b32_e32 v18, v156
	v_mov_b32_e32 v19, v157
	s_nop 0
	v_mov_b32_e32 v14, v158
	v_mov_b32_e32 v15, v159
	v_mov_b32_e32 v16, v160
	v_mov_b32_e32 v17, v161
	v_pk_mul_f32 v[20:21], v[40:41], v[36:37] op_sel_hi:[0,1]
	s_waitcnt vmcnt(1)
	v_lshlrev_b32_e32 v26, 16, v18
	v_and_b32_e32 v27, 0xffff0000, v18
	v_lshlrev_b32_e32 v18, 16, v19
	v_and_b32_e32 v19, 0xffff0000, v19
	v_pk_fma_f32 v[14:15], v[14:15], v[20:21], v[26:27]
	v_pk_fma_f32 v[16:17], v[16:17], v[22:23], v[18:19]
	global_store_dwordx4 v[28:29], v[14:17], off offset:2048
	v_mov_b32_e32 v18, v162
	v_mov_b32_e32 v19, v163
	s_nop 0
	v_mov_b32_e32 v14, v164
	v_mov_b32_e32 v15, v165
	v_mov_b32_e32 v16, v166
	v_mov_b32_e32 v17, v167
	v_pk_mul_f32 v[20:21], v[40:41], v[38:39] op_sel_hi:[0,1]
	v_pk_mul_f32 v[22:23], v[40:41], v[24:25] op_sel_hi:[0,1]
	v_lshl_add_u64 v[4:5], v[4:5], 0, s[4:5]
	s_waitcnt vmcnt(1)
	v_lshlrev_b32_e32 v24, 16, v18
	v_and_b32_e32 v25, 0xffff0000, v18
	v_lshlrev_b32_e32 v18, 16, v19
	v_and_b32_e32 v19, 0xffff0000, v19
	v_pk_fma_f32 v[14:15], v[14:15], v[20:21], v[24:25]
	v_pk_fma_f32 v[16:17], v[16:17], v[22:23], v[18:19]
	global_store_dwordx4 v[28:29], v[14:17], off offset:3072
	s_cbranch_scc1 .LBB0_1923
